# v23 plus SWA attention output stored as 16-byte pieces after a permlane32 exchange (was 8-byte pieces)
# speedup vs baseline: 1.0139x; 1.0130x over previous
.LBB0_252:
	s_or_b64 exec, exec, s[48:49]
	v_mov_b32_e32 v33, v32
	s_nop 1
	v_permlane32_swap_b32_e32 v32, v33
	v_add_f32_e32 v32, v32, v33
	v_div_scale_f32 v33, s[0:1], v32, v32, 1.0
	v_rcp_f32_e32 v34, v33
	v_mov_b32_e32 v81, v65
	v_mov_b32_e32 v69, v65
	v_mov_b32_e32 v71, v65
	v_fma_f32 v35, -v33, v34, 1.0
	v_fmac_f32_e32 v34, v35, v34
	v_div_scale_f32 v35, vcc, 1.0, v32, 1.0
	v_mul_f32_e32 v36, v35, v34
	v_fma_f32 v37, -v33, v36, v35
	v_fmac_f32_e32 v36, v37, v34
	v_fma_f32 v33, -v33, v36, v35
	v_div_fmas_f32 v33, v33, v34, v36
	v_lshlrev_b64 v[34:35], 11, v[78:79]
	v_lshl_add_u64 v[34:35], s[36:37], 0, v[34:35]
	v_div_fixup_f32 v32, v33, v32, 1.0
	v_lshl_add_u64 v[34:35], v[34:35], 0, v[80:81]
	v_lshl_add_u64 v[36:37], v[34:35], 0, s[44:45]
	v_pk_mul_f32 v[0:1], v[0:1], v[32:33] op_sel_hi:[1,0]
	v_pk_mul_f32 v[2:3], v[2:3], v[32:33] op_sel_hi:[1,0]
	v_cvt_pk_bf16_f32 v162, v0, v1
	v_cvt_pk_bf16_f32 v163, v2, v3
	v_pk_mul_f32 v[4:5], v[4:5], v[32:33] op_sel_hi:[1,0]
	v_pk_mul_f32 v[6:7], v[6:7], v[32:33] op_sel_hi:[1,0]
	v_cvt_pk_bf16_f32 v164, v4, v5
	v_cvt_pk_bf16_f32 v165, v6, v7
	v_pk_mul_f32 v[8:9], v[8:9], v[32:33] op_sel_hi:[1,0]
	v_pk_mul_f32 v[10:11], v[10:11], v[32:33] op_sel_hi:[1,0]
	v_cvt_pk_bf16_f32 v166, v8, v9
	v_cvt_pk_bf16_f32 v167, v10, v11
	v_pk_mul_f32 v[12:13], v[12:13], v[32:33] op_sel_hi:[1,0]
	v_pk_mul_f32 v[14:15], v[14:15], v[32:33] op_sel_hi:[1,0]
	v_cvt_pk_bf16_f32 v168, v12, v13
	v_cvt_pk_bf16_f32 v169, v14, v15
	v_pk_mul_f32 v[16:17], v[16:17], v[32:33] op_sel_hi:[1,0]
	v_pk_mul_f32 v[18:19], v[18:19], v[32:33] op_sel_hi:[1,0]
	v_cvt_pk_bf16_f32 v170, v16, v17
	v_cvt_pk_bf16_f32 v171, v18, v19
	v_pk_mul_f32 v[20:21], v[20:21], v[32:33] op_sel_hi:[1,0]
	v_pk_mul_f32 v[22:23], v[22:23], v[32:33] op_sel_hi:[1,0]
	v_cvt_pk_bf16_f32 v172, v20, v21
	v_cvt_pk_bf16_f32 v173, v22, v23
	v_pk_mul_f32 v[24:25], v[24:25], v[32:33] op_sel_hi:[1,0]
	v_pk_mul_f32 v[26:27], v[26:27], v[32:33] op_sel_hi:[1,0]
	v_cvt_pk_bf16_f32 v174, v24, v25
	v_cvt_pk_bf16_f32 v175, v26, v27
	v_pk_mul_f32 v[28:29], v[28:29], v[32:33] op_sel_hi:[1,0]
	v_pk_mul_f32 v[30:31], v[30:31], v[32:33] op_sel_hi:[1,0]
	v_cvt_pk_bf16_f32 v176, v28, v29
	v_cvt_pk_bf16_f32 v177, v30, v31
	s_nop 1
	v_permlane32_swap_b32_e32 v162, v164
	v_permlane32_swap_b32_e32 v163, v165
	v_permlane32_swap_b32_e32 v166, v168
	v_permlane32_swap_b32_e32 v167, v169
	v_permlane32_swap_b32_e32 v170, v172
	v_permlane32_swap_b32_e32 v171, v173
	v_permlane32_swap_b32_e32 v174, v176
	v_permlane32_swap_b32_e32 v175, v177
	v_lshl_add_u64 v[2:3], v[68:69], 1, v[36:37]
	global_store_dwordx4 v[2:3], v[162:165], off
	global_store_dwordx4 v[2:3], v[166:169], off offset:32
	global_store_dwordx4 v[2:3], v[170:173], off offset:64
	global_store_dwordx4 v[2:3], v[174:177], off offset:96
	v_mov_b32_e32 v73, v65
	v_mov_b32_e32 v75, v65
	v_add_u32_e32 v88, s84, v88
	v_cmp_lt_i32_e32 vcc, s57, v88
	s_or_b64 s[30:31], vcc, s[30:31]
	v_add_u32_e32 v92, s52, v92
	s_andn2_b64 exec, exec, s[30:31]
	s_cbranch_execz .LBB0_257
